# prologue keeps exactly one weight-transposition item per wave (2048); the rest deferred to tail slots
# baseline (speedup 1.0000x reference)
; #define LAS __attribute__((address_space(3)))
; DEVI unsigned cvtpk(float lo, float hi) { f32x2_t v = {lo, hi}; bf16x2_t b = __builtin_convertvector(v, bf16x2_t); return __builtin_bit_cast(unsigned, b); }
; DEVI const float* IN(int i) { return *(const float* const __attribute__((address_space(4)))*)(kargs() + 8 * i); }
; DEVI void tr_item(const float* W, int N, int K, const float* gain, bf16_t* WT, int dest0, LAS float* scr, int k0, int n0, int lane) {
; #pragma unroll
;     for (int i = 0; i < 32; ++i) { const int kk = 2 * i + (lane >> 5); float v = W[(size_t)(k0 + kk) * N + n0 + (lane & 31)]; if (gain) v *= gain[k0 + kk]; scr[kk * 33 + (lane & 31)] = v; }
;     asm volatile("s_waitcnt lgkmcnt(0)" ::: "memory");
;     const int c = lane & 7;
; #pragma unroll
;     for (int j = 0; j < 4; ++j) { const int n = (lane >> 3) + 8 * j; const LAS float* s = scr + (8 * c) * 33 + n;
;         u32x4 o; o.x = cvtpk(s[0], s[33]); o.y = cvtpk(s[2 * 33], s[3 * 33]); o.z = cvtpk(s[4 * 33], s[5 * 33]); o.w = cvtpk(s[6 * 33], s[7 * 33]);
;         *(u32x4*)(WT + (size_t)(dest0 + n) * K + k0 + 8 * c) = o; }
;     asm volatile("s_waitcnt lgkmcnt(0)" ::: "memory");
; }
; DEVI void prologue(int wv, LAS unsigned char* lds) {
;     ...
;     constexpr int I_IN = 16 * 101, I_UQ = 6 * 24, I_KV = 4 * 32, I_A = 8 * 32, I_O = 16 * 32, I_UP = 16 * 128, I_DN = 64 * 32;
;     constexpr int I_L = I_IN + I_UQ + 2 * I_KV + I_A + I_O + I_UP + I_DN;
;     for (int it = gw; it < 2 * I_L; it += NGW) {
;         const int l = it / I_L; int r = it % I_L;
;         unsigned char* wl = ws + O_W + (size_t)l * W_LAYER;
;         if (r < I_IN) { const int kb = r / 101, nb = r % 101, n0 = nb * 32;
;             const int d0 = n0 < 384 ? n0 : n0 < 640 ? 512 + (n0 - 384) : n0 < 672 ? 384 + (n0 - 640) : n0 < 1184 ? 768 + (n0 - 672) : n0 < 2208 ? 1280 + (n0 - 1184) : 2304 + (n0 - 2208);
;             tr_item(IN(6) + (size_t)l * 1024 * 3232, 3232, 1024, IN(5) + l * 1024, (bf16_t*)(wl + W_IN), d0, scr, kb * 64, n0, lane); continue; }
.LBB0_23:
	s_or_b64 exec, exec, s[2:3]
	s_mov_b32 s16, s85
	s_mov_b32 s18, s95
	s_mov_b64 s[6:7], s[0:1]
	s_waitcnt lgkmcnt(0)
	s_barrier
	v_mbcnt_lo_u32_b32 v64, -1, 0
	v_mbcnt_hi_u32_b32 v64, -1, v64
	v_lshl_or_b32 v64, s33, 6, v64
	s_load_dwordx2 s[20:21], s[6:7], 0xb0
	v_readfirstlane_b32 s2, v64
	s_ashr_i32 s2, s2, 6
	s_lshl_b32 s3, s18, 3
	v_and_b32_e32 v34, 63, v64
	s_add_i32 s4, s3, s2
	s_lshl_b32 s14, s16, 3
	s_ashr_i32 s17, s16, 31
	v_ashrrev_i32_e32 v65, 31, v64
	s_movk_i32 s52, 0x35bf
	s_cmp_eq_u32 s16, 0x100
	s_cselect_b32 s52, 0x7ff, s52
	s_cmp_gt_i32 s4, s52
	v_lshlrev_b32_e32 v66, 3, v34
	s_cbranch_scc1 .LBB0_328
	v_lshrrev_b32_e32 v0, 5, v34
	s_movk_i32 s3, 0x84
	v_mov_b32_e32 v1, 0x108
	v_mad_u32_u24 v13, v0, s3, v1
	v_mov_b32_e32 v1, 0x210
	v_mad_u32_u24 v15, v0, s3, v1
	v_mov_b32_e32 v1, 0x318
	v_mad_u32_u24 v17, v0, s3, v1
	v_mov_b32_e32 v1, 0x420
	v_mad_u32_u24 v19, v0, s3, v1
	v_mov_b32_e32 v1, 0x528
	v_mad_u32_u24 v21, v0, s3, v1
	v_mov_b32_e32 v1, 0x630
	v_mad_u32_u24 v23, v0, s3, v1
	v_mov_b32_e32 v1, 0x738
	v_mad_u32_u24 v25, v0, s3, v1
	v_mov_b32_e32 v1, 0x840
	v_mad_u32_u24 v27, v0, s3, v1
	v_mov_b32_e32 v1, 0x948
	v_mad_u32_u24 v29, v0, s3, v1
	v_mov_b32_e32 v1, 0xa50
	v_mad_u32_u24 v31, v0, s3, v1
	v_mov_b32_e32 v1, 0xb58
	v_mad_u32_u24 v33, v0, s3, v1
	v_mov_b32_e32 v1, 0xc60
	v_mad_u32_u24 v36, v0, s3, v1
	v_mov_b32_e32 v1, 0xd68
	v_mad_u32_u24 v38, v0, s3, v1
	v_mov_b32_e32 v1, 0xe70
	v_mad_u32_u24 v40, v0, s3, v1
	v_mov_b32_e32 v1, 0xf78
	v_mad_u32_u24 v42, v0, s3, v1
	v_mov_b32_e32 v1, 0x1080
	v_mad_u32_u24 v44, v0, s3, v1
	v_mov_b32_e32 v1, 0x1188
	v_mad_u32_u24 v46, v0, s3, v1
	v_mov_b32_e32 v1, 0x1290
	v_mad_u32_u24 v48, v0, s3, v1
	v_mov_b32_e32 v1, 0x1398
	v_mad_u32_u24 v50, v0, s3, v1
	v_mov_b32_e32 v1, 0x14a0
	v_mad_u32_u24 v51, v0, s3, v1
	v_mov_b32_e32 v1, 0x15a8
	v_mad_u32_u24 v52, v0, s3, v1
	v_mov_b32_e32 v1, 0x16b0
	s_mulk_i32 s2, 0x2100
	v_mad_u32_u24 v53, v0, s3, v1
	v_mov_b32_e32 v1, 0x17b8
	v_lshrrev_b32_e32 v55, 3, v34
	v_and_b32_e32 v6, 56, v66
	s_add_i32 s2, s2, 0
	v_mad_u32_u24 v54, v0, s3, v1
	v_mul_u32_u24_e32 v1, 0x84, v6
	v_lshlrev_b32_e32 v4, 2, v55
	s_waitcnt lgkmcnt(0)
	s_add_u32 s5, s20, 0x390800
	v_and_b32_e32 v2, 31, v64
	v_mov_b32_e32 v5, 0
	v_add3_u32 v56, s2, v1, v4
	v_mov_b32_e32 v1, 0x18c0
	s_mov_b32 s7, 0
	s_addc_u32 s15, s21, 0
	v_lshl_add_u32 v3, v2, 2, s2
	v_mul_u32_u24_e32 v7, 0x84, v0
	v_or_b32_e32 v12, 2, v0
	v_or_b32_e32 v14, 4, v0
	v_or_b32_e32 v16, 6, v0
	v_or_b32_e32 v18, 8, v0
	v_or_b32_e32 v20, 10, v0
	v_or_b32_e32 v22, 12, v0
	v_or_b32_e32 v24, 14, v0
	v_or_b32_e32 v26, 16, v0
	v_or_b32_e32 v28, 18, v0
	v_or_b32_e32 v30, 20, v0
	v_or_b32_e32 v32, 22, v0
	v_or_b32_e32 v35, 24, v0
	v_or_b32_e32 v37, 26, v0
	v_or_b32_e32 v39, 28, v0
	v_or_b32_e32 v41, 30, v0
	v_or_b32_e32 v43, 32, v0
	v_or_b32_e32 v45, 34, v0
	v_or_b32_e32 v47, 36, v0
	v_or_b32_e32 v49, 38, v0
	v_mad_u32_u24 v57, v0, s3, v1
	v_mov_b32_e32 v1, v5
	s_lshl_b32 s19, s4, 1
	s_lshl_b32 s40, s16, 4
	s_lshl_b32 s41, s4, 5
	s_lshl_b32 s42, s16, 8
	s_mov_b64 s[8:9], 0x1410000
	s_mov_b64 s[10:11], 0xc10000
	s_mov_b64 s[12:13], 0xa10000
	s_mov_b64 s[22:23], 0x810000
	s_movk_i32 s43, 0xf920
	s_movk_i32 s44, 0x300
	s_movk_i32 s45, 0xc00
	s_mov_b64 s[24:25], 0x680000
	s_mov_b32 s46, s4
	v_or_b32_e32 v58, 40, v0
	v_or_b32_e32 v59, 42, v0
	v_or_b32_e32 v60, 44, v0
	v_or_b32_e32 v61, 46, v0
	v_or_b32_e32 v62, 48, v0
	v_or_b32_e32 v63, 50, v0
	v_or_b32_e32 v67, 52, v0
	v_or_b32_e32 v68, 54, v0
	v_or_b32_e32 v69, 56, v0
	v_or_b32_e32 v70, 58, v0
	v_or_b32_e32 v71, 60, v0
	v_or_b32_e32 v72, 62, v0
	v_or_b32_e32 v73, 8, v55
	v_or_b32_e32 v74, 16, v55
	v_or_b32_e32 v75, 24, v55
	s_branch .LBB0_28

; DEVI const float* IN(int i) { return *(const float* const __attribute__((address_space(4)))*)(kargs() + 8 * i); }
; DEVI void prologue(int wv, LAS unsigned char* lds) {
;     ...
;     for (int it = gw; it < 2 * I_L; it += NGW) {
;         const int l = it / I_L; int r = it % I_L;
;         unsigned char* wl = ws + O_W + (size_t)l * W_LAYER;
;         if (r < I_IN) { const int kb = r / 101, nb = r % 101, n0 = nb * 32;
;             const int d0 = n0 < 384 ? n0 : n0 < 640 ? 512 + (n0 - 384) : n0 < 672 ? 384 + (n0 - 640) : n0 < 1184 ? 768 + (n0 - 672) : n0 < 2208 ? 1280 + (n0 - 1184) : 2304 + (n0 - 2208);
;             tr_item(IN(6) + (size_t)l * 1024 * 3232, 3232, 1024, IN(5) + l * 1024, (bf16_t*)(wl + W_IN), d0, scr, kb * 64, n0, lane); continue; }
;         r -= I_IN;
;         if (r < I_UQ) { const int kb = r / 24, nb = r % 24, n0 = nb * 32, hd = n0 / 96, dim0 = n0 % 96;
;             const int d0 = dim0 < 64 ? 256 * (hd >> 2) + 128 * (dim0 >> 5) + 32 * (hd & 3) : 512 + 128 * (hd >> 2) + 32 * (hd & 3);
;             tr_item(IN(9) + (size_t)l * 384 * 768, 768, 384, IN(7) + l * 384, (bf16_t*)(wl + W_UQ), d0, scr, kb * 64, n0, lane); continue; }
;         r -= I_UQ;
;         if (r < 2 * I_KV) { const int fold = r < I_KV; if (!fold) r -= I_KV;
;             const int kb = r / 32, nb = r % 32, n0 = nb * 32, hd = n0 / 128, dim0 = n0 % 128;
;             const bool isk = dim0 < 64;
;             const int d0 = isk ? 256 * (hd >> 2) + 128 * (dim0 >> 5) + 32 * (hd & 3) : hd * 64 + (dim0 - 64);
;             bf16_t* dst = (bf16_t*)(wl + (fold ? (isk ? W_K : W_V) : (isk ? W_KC : W_VC)));
;             tr_item(IN(10) + (size_t)l * 256 * 1024, 1024, 256, fold ? IN(8) + l * 256 : nullptr, dst, d0, scr, kb * 64, n0, lane); continue; }
;         r -= 2 * I_KV;
;         if (r < I_A) { tr_item(IN(13) + (size_t)l * 512 * 1024, 1024, 512, nullptr, (bf16_t*)(wl + W_A), (r % 32) * 32, scr, (r / 32) * 64, (r % 32) * 32, lane); continue; }
;         r -= I_A;
;         if (r < I_O) { tr_item(IN(17) + (size_t)l * 1024 * 1024, 1024, 1024, nullptr, (bf16_t*)(wl + W_O), (r % 32) * 32, scr, (r / 32) * 64, (r % 32) * 32, lane); continue; }
;         r -= I_O;
;         if (r < I_UP) { tr_item(IN(19) + (size_t)l * 1024 * 4096, 4096, 1024, IN(18) + l * 1024, (bf16_t*)(wl + W_UP), (r % 128) * 32, scr, (r / 128) * 64, (r % 128) * 32, lane); continue; }
;         r -= I_UP;
.LBB0_715:
	s_waitcnt vmcnt(0) lgkmcnt(0)
	s_load_dword vcc_lo, s[0:1], 0xb8
	v_readlane_b32 vcc_hi, v255, 5
	s_waitcnt lgkmcnt(0)
	s_cmp_lg_u32 vcc_lo, 0x100
	s_cbranch_scc1 .Lsj_skip1
	s_sub_i32 vcc_hi, vcc_hi, 154
	s_and_b32 vcc_hi, vcc_hi, 0xff
	s_cmp_ge_u32 vcc_hi, 102
	s_cbranch_scc1 .Lsj_skip1
	v_readlane_b32 vcc_lo, v255, 0
	v_writelane_b32 v201, s0, 0
	v_writelane_b32 v201, s1, 1
	v_writelane_b32 v201, s2, 2
	v_writelane_b32 v201, s3, 3
	v_writelane_b32 v201, s4, 4
	v_writelane_b32 v201, s5, 5
	v_writelane_b32 v201, s6, 6
	v_writelane_b32 v201, s7, 7
	v_writelane_b32 v201, s8, 8
	v_writelane_b32 v201, s9, 9
	v_writelane_b32 v201, s10, 10
	v_writelane_b32 v201, s11, 11
	v_writelane_b32 v201, s12, 12
	v_writelane_b32 v201, s13, 13
	v_writelane_b32 v201, s14, 14
	v_writelane_b32 v201, s15, 15
	v_writelane_b32 v201, s16, 16
	v_writelane_b32 v201, s17, 17
	v_writelane_b32 v201, s18, 18
	v_writelane_b32 v201, s19, 19
	v_writelane_b32 v201, s20, 20
	v_writelane_b32 v201, s21, 21
	v_writelane_b32 v201, s22, 22
	v_writelane_b32 v201, s23, 23
	v_writelane_b32 v201, s24, 24
	v_writelane_b32 v201, s25, 25
	v_writelane_b32 v201, s26, 26
	v_writelane_b32 v201, s27, 27
	v_writelane_b32 v201, s28, 28
	v_writelane_b32 v201, s29, 29
	v_writelane_b32 v201, s30, 30
	v_writelane_b32 v201, s31, 31
	v_writelane_b32 v201, s32, 32
	v_writelane_b32 v201, s33, 33
	v_writelane_b32 v201, s34, 34
	v_writelane_b32 v201, s35, 35
	v_writelane_b32 v201, s36, 36
	v_writelane_b32 v201, s37, 37
	v_writelane_b32 v201, s38, 38
	v_writelane_b32 v201, s39, 39
	v_writelane_b32 v201, s40, 40
	v_writelane_b32 v201, s41, 41
	v_writelane_b32 v201, s42, 42
	v_writelane_b32 v201, s43, 43
	v_writelane_b32 v201, s44, 44
	v_writelane_b32 v201, s45, 45
	v_writelane_b32 v201, s46, 46
	v_writelane_b32 v201, s47, 47
	v_writelane_b32 v201, s48, 48
	v_writelane_b32 v201, s49, 49
	v_writelane_b32 v201, s50, 50
	v_writelane_b32 v201, s51, 51
	v_writelane_b32 v201, s52, 52
	v_writelane_b32 v201, s53, 53
	v_writelane_b32 v201, s54, 54
	v_writelane_b32 v201, s55, 55
	v_writelane_b32 v201, s56, 56
	v_writelane_b32 v201, s57, 57
	v_writelane_b32 v201, s58, 58
	v_writelane_b32 v201, s59, 59
	v_writelane_b32 v201, s60, 60
	v_writelane_b32 v201, s61, 61
	v_writelane_b32 v201, s62, 62
	v_writelane_b32 v201, s63, 63
	v_writelane_b32 v202, s64, 0
	v_writelane_b32 v202, s65, 1
	v_writelane_b32 v202, s66, 2
	v_writelane_b32 v202, s67, 3
	v_writelane_b32 v202, s68, 4
	v_writelane_b32 v202, s69, 5
	v_writelane_b32 v202, s70, 6
	v_writelane_b32 v202, s71, 7
	v_writelane_b32 v202, s72, 8
	v_writelane_b32 v202, s73, 9
	v_writelane_b32 v202, s74, 10
	v_writelane_b32 v202, s75, 11
	v_writelane_b32 v202, s76, 12
	v_writelane_b32 v202, s77, 13
	v_writelane_b32 v202, s78, 14
	v_writelane_b32 v202, s79, 15
	v_writelane_b32 v202, s80, 16
	v_writelane_b32 v202, s81, 17
	v_writelane_b32 v202, s82, 18
	v_writelane_b32 v202, s83, 19
	v_writelane_b32 v202, s84, 20
	v_writelane_b32 v202, s85, 21
	v_writelane_b32 v202, s86, 22
	v_writelane_b32 v202, s87, 23
	v_writelane_b32 v202, s88, 24
	v_writelane_b32 v202, s89, 25
	v_writelane_b32 v202, s90, 26
	v_writelane_b32 v202, s91, 27
	v_writelane_b32 v202, s92, 28
	v_writelane_b32 v202, s93, 29
	v_writelane_b32 v202, s94, 30
	v_writelane_b32 v202, s95, 31
	v_writelane_b32 v202, s96, 32
	v_writelane_b32 v202, s97, 33
	v_writelane_b32 v202, s98, 34
	v_writelane_b32 v202, s99, 35
	v_mov_b32_e32 v200, v1
	s_mov_b32 s54, 0
	s_mov_b32 s52, -1
	s_cmp_lg_u32 vcc_lo, 0
	s_cbranch_scc0 .Lsj_par1
	s_mov_b32 s54, 2048
	s_mov_b32 s52, 2863

; DEVI const float* IN(int i) { return *(const float* const __attribute__((address_space(4)))*)(kargs() + 8 * i); }
; DEVI void prologue(int wv, LAS unsigned char* lds) {
;     ...
;     for (int it = gw; it < 2 * I_L; it += NGW) {
;         const int l = it / I_L; int r = it % I_L;
;         unsigned char* wl = ws + O_W + (size_t)l * W_LAYER;
;         if (r < I_IN) { const int kb = r / 101, nb = r % 101, n0 = nb * 32;
;             const int d0 = n0 < 384 ? n0 : n0 < 640 ? 512 + (n0 - 384) : n0 < 672 ? 384 + (n0 - 640) : n0 < 1184 ? 768 + (n0 - 672) : n0 < 2208 ? 1280 + (n0 - 1184) : 2304 + (n0 - 2208);
;             tr_item(IN(6) + (size_t)l * 1024 * 3232, 3232, 1024, IN(5) + l * 1024, (bf16_t*)(wl + W_IN), d0, scr, kb * 64, n0, lane); continue; }
;         r -= I_IN;
;         if (r < I_UQ) { const int kb = r / 24, nb = r % 24, n0 = nb * 32, hd = n0 / 96, dim0 = n0 % 96;
;             const int d0 = dim0 < 64 ? 256 * (hd >> 2) + 128 * (dim0 >> 5) + 32 * (hd & 3) : 512 + 128 * (hd >> 2) + 32 * (hd & 3);
;             tr_item(IN(9) + (size_t)l * 384 * 768, 768, 384, IN(7) + l * 384, (bf16_t*)(wl + W_UQ), d0, scr, kb * 64, n0, lane); continue; }
;         r -= I_UQ;
;         if (r < 2 * I_KV) { const int fold = r < I_KV; if (!fold) r -= I_KV;
;             const int kb = r / 32, nb = r % 32, n0 = nb * 32, hd = n0 / 128, dim0 = n0 % 128;
;             const bool isk = dim0 < 64;
;             const int d0 = isk ? 256 * (hd >> 2) + 128 * (dim0 >> 5) + 32 * (hd & 3) : hd * 64 + (dim0 - 64);
;             bf16_t* dst = (bf16_t*)(wl + (fold ? (isk ? W_K : W_V) : (isk ? W_KC : W_VC)));
;             tr_item(IN(10) + (size_t)l * 256 * 1024, 1024, 256, fold ? IN(8) + l * 256 : nullptr, dst, d0, scr, kb * 64, n0, lane); continue; }
;         r -= 2 * I_KV;
;         if (r < I_A) { tr_item(IN(13) + (size_t)l * 512 * 1024, 1024, 512, nullptr, (bf16_t*)(wl + W_A), (r % 32) * 32, scr, (r / 32) * 64, (r % 32) * 32, lane); continue; }
;         r -= I_A;
;         if (r < I_O) { tr_item(IN(17) + (size_t)l * 1024 * 1024, 1024, 1024, nullptr, (bf16_t*)(wl + W_O), (r % 32) * 32, scr, (r / 32) * 64, (r % 32) * 32, lane); continue; }
;         r -= I_O;
;         if (r < I_UP) { tr_item(IN(19) + (size_t)l * 1024 * 4096, 4096, 1024, IN(18) + l * 1024, (bf16_t*)(wl + W_UP), (r % 128) * 32, scr, (r / 128) * 64, (r % 128) * 32, lane); continue; }
;         r -= I_UP;
.LBB0_1230:
	s_waitcnt vmcnt(0) lgkmcnt(0)
	s_load_dword vcc_lo, s[0:1], 0xb8
	v_readlane_b32 vcc_hi, v255, 5
	s_waitcnt lgkmcnt(0)
	s_cmp_lg_u32 vcc_lo, 0x100
	s_cbranch_scc1 .Lsj_skip2
	s_sub_i32 vcc_hi, vcc_hi, 36
	s_and_b32 vcc_hi, vcc_hi, 0xff
	s_cmp_ge_u32 vcc_hi, 118
	s_cbranch_scc1 .Lsj_skip2
	v_readlane_b32 vcc_lo, v255, 0
	v_writelane_b32 v201, s0, 0
	v_writelane_b32 v201, s1, 1
	v_writelane_b32 v201, s2, 2
	v_writelane_b32 v201, s3, 3
	v_writelane_b32 v201, s4, 4
	v_writelane_b32 v201, s5, 5
	v_writelane_b32 v201, s6, 6
	v_writelane_b32 v201, s7, 7
	v_writelane_b32 v201, s8, 8
	v_writelane_b32 v201, s9, 9
	v_writelane_b32 v201, s10, 10
	v_writelane_b32 v201, s11, 11
	v_writelane_b32 v201, s12, 12
	v_writelane_b32 v201, s13, 13
	v_writelane_b32 v201, s14, 14
	v_writelane_b32 v201, s15, 15
	v_writelane_b32 v201, s16, 16
	v_writelane_b32 v201, s17, 17
	v_writelane_b32 v201, s18, 18
	v_writelane_b32 v201, s19, 19
	v_writelane_b32 v201, s20, 20
	v_writelane_b32 v201, s21, 21
	v_writelane_b32 v201, s22, 22
	v_writelane_b32 v201, s23, 23
	v_writelane_b32 v201, s24, 24
	v_writelane_b32 v201, s25, 25
	v_writelane_b32 v201, s26, 26
	v_writelane_b32 v201, s27, 27
	v_writelane_b32 v201, s28, 28
	v_writelane_b32 v201, s29, 29
	v_writelane_b32 v201, s30, 30
	v_writelane_b32 v201, s31, 31
	v_writelane_b32 v201, s32, 32
	v_writelane_b32 v201, s33, 33
	v_writelane_b32 v201, s34, 34
	v_writelane_b32 v201, s35, 35
	v_writelane_b32 v201, s36, 36
	v_writelane_b32 v201, s37, 37
	v_writelane_b32 v201, s38, 38
	v_writelane_b32 v201, s39, 39
	v_writelane_b32 v201, s40, 40
	v_writelane_b32 v201, s41, 41
	v_writelane_b32 v201, s42, 42
	v_writelane_b32 v201, s43, 43
	v_writelane_b32 v201, s44, 44
	v_writelane_b32 v201, s45, 45
	v_writelane_b32 v201, s46, 46
	v_writelane_b32 v201, s47, 47
	v_writelane_b32 v201, s48, 48
	v_writelane_b32 v201, s49, 49
	v_writelane_b32 v201, s50, 50
	v_writelane_b32 v201, s51, 51
	v_writelane_b32 v201, s52, 52
	v_writelane_b32 v201, s53, 53
	v_writelane_b32 v201, s54, 54
	v_writelane_b32 v201, s55, 55
	v_writelane_b32 v201, s56, 56
	v_writelane_b32 v201, s57, 57
	v_writelane_b32 v201, s58, 58
	v_writelane_b32 v201, s59, 59
	v_writelane_b32 v201, s60, 60
	v_writelane_b32 v201, s61, 61
	v_writelane_b32 v201, s62, 62
	v_writelane_b32 v201, s63, 63
	v_writelane_b32 v202, s64, 0
	v_writelane_b32 v202, s65, 1
	v_writelane_b32 v202, s66, 2
	v_writelane_b32 v202, s67, 3
	v_writelane_b32 v202, s68, 4
	v_writelane_b32 v202, s69, 5
	v_writelane_b32 v202, s70, 6
	v_writelane_b32 v202, s71, 7
	v_writelane_b32 v202, s72, 8
	v_writelane_b32 v202, s73, 9
	v_writelane_b32 v202, s74, 10
	v_writelane_b32 v202, s75, 11
	v_writelane_b32 v202, s76, 12
	v_writelane_b32 v202, s77, 13
	v_writelane_b32 v202, s78, 14
	v_writelane_b32 v202, s79, 15
	v_writelane_b32 v202, s80, 16
	v_writelane_b32 v202, s81, 17
	v_writelane_b32 v202, s82, 18
	v_writelane_b32 v202, s83, 19
	v_writelane_b32 v202, s84, 20
	v_writelane_b32 v202, s85, 21
	v_writelane_b32 v202, s86, 22
	v_writelane_b32 v202, s87, 23
	v_writelane_b32 v202, s88, 24
	v_writelane_b32 v202, s89, 25
	v_writelane_b32 v202, s90, 26
	v_writelane_b32 v202, s91, 27
	v_writelane_b32 v202, s92, 28
	v_writelane_b32 v202, s93, 29
	v_writelane_b32 v202, s94, 30
	v_writelane_b32 v202, s95, 31
	v_writelane_b32 v202, s96, 32
	v_writelane_b32 v202, s97, 33
	v_writelane_b32 v202, s98, 34
	v_writelane_b32 v202, s99, 35
	v_mov_b32_e32 v200, v1
	s_mov_b32 s54, 9664
	s_mov_b32 s52, 10607
	s_cmp_lg_u32 vcc_lo, 0
	s_cbranch_scc0 .Lsj_par2
	s_mov_b32 s54, 2864
	s_mov_b32 s52, 3807

; DEVI const float* IN(int i) { return *(const float* const __attribute__((address_space(4)))*)(kargs() + 8 * i); }
; DEVI void prologue(int wv, LAS unsigned char* lds) {
;     ...
;     for (int it = gw; it < 2 * I_L; it += NGW) {
;         const int l = it / I_L; int r = it % I_L;
;         unsigned char* wl = ws + O_W + (size_t)l * W_LAYER;
;         if (r < I_IN) { const int kb = r / 101, nb = r % 101, n0 = nb * 32;
;             const int d0 = n0 < 384 ? n0 : n0 < 640 ? 512 + (n0 - 384) : n0 < 672 ? 384 + (n0 - 640) : n0 < 1184 ? 768 + (n0 - 672) : n0 < 2208 ? 1280 + (n0 - 1184) : 2304 + (n0 - 2208);
;             tr_item(IN(6) + (size_t)l * 1024 * 3232, 3232, 1024, IN(5) + l * 1024, (bf16_t*)(wl + W_IN), d0, scr, kb * 64, n0, lane); continue; }
;         r -= I_IN;
;         if (r < I_UQ) { const int kb = r / 24, nb = r % 24, n0 = nb * 32, hd = n0 / 96, dim0 = n0 % 96;
;             const int d0 = dim0 < 64 ? 256 * (hd >> 2) + 128 * (dim0 >> 5) + 32 * (hd & 3) : 512 + 128 * (hd >> 2) + 32 * (hd & 3);
;             tr_item(IN(9) + (size_t)l * 384 * 768, 768, 384, IN(7) + l * 384, (bf16_t*)(wl + W_UQ), d0, scr, kb * 64, n0, lane); continue; }
;         r -= I_UQ;
;         if (r < 2 * I_KV) { const int fold = r < I_KV; if (!fold) r -= I_KV;
;             const int kb = r / 32, nb = r % 32, n0 = nb * 32, hd = n0 / 128, dim0 = n0 % 128;
;             const bool isk = dim0 < 64;
;             const int d0 = isk ? 256 * (hd >> 2) + 128 * (dim0 >> 5) + 32 * (hd & 3) : hd * 64 + (dim0 - 64);
;             bf16_t* dst = (bf16_t*)(wl + (fold ? (isk ? W_K : W_V) : (isk ? W_KC : W_VC)));
;             tr_item(IN(10) + (size_t)l * 256 * 1024, 1024, 256, fold ? IN(8) + l * 256 : nullptr, dst, d0, scr, kb * 64, n0, lane); continue; }
;         r -= 2 * I_KV;
;         if (r < I_A) { tr_item(IN(13) + (size_t)l * 512 * 1024, 1024, 512, nullptr, (bf16_t*)(wl + W_A), (r % 32) * 32, scr, (r / 32) * 64, (r % 32) * 32, lane); continue; }
;         r -= I_A;
;         if (r < I_O) { tr_item(IN(17) + (size_t)l * 1024 * 1024, 1024, 1024, nullptr, (bf16_t*)(wl + W_O), (r % 32) * 32, scr, (r / 32) * 64, (r % 32) * 32, lane); continue; }
;         r -= I_O;
;         if (r < I_UP) { tr_item(IN(19) + (size_t)l * 1024 * 4096, 4096, 1024, IN(18) + l * 1024, (bf16_t*)(wl + W_UP), (r % 128) * 32, scr, (r / 128) * 64, (r % 128) * 32, lane); continue; }
;         r -= I_UP;
.LBB0_1468:
	s_waitcnt vmcnt(0) lgkmcnt(0)
	s_load_dword vcc_lo, s[0:1], 0xb8
	v_readlane_b32 vcc_hi, v255, 5
	s_waitcnt lgkmcnt(0)
	s_cmp_lg_u32 vcc_lo, 0x100
	s_cbranch_scc1 .Lsj_skip4
	s_sub_i32 vcc_hi, vcc_hi, 48
	s_and_b32 vcc_hi, vcc_hi, 0xff
	s_cmp_ge_u32 vcc_hi, 248
	s_cbranch_scc1 .Lsj_skip4
	v_readlane_b32 vcc_lo, v255, 0
	v_writelane_b32 v201, s0, 0
	v_writelane_b32 v201, s1, 1
	v_writelane_b32 v201, s2, 2
	v_writelane_b32 v201, s3, 3
	v_writelane_b32 v201, s4, 4
	v_writelane_b32 v201, s5, 5
	v_writelane_b32 v201, s6, 6
	v_writelane_b32 v201, s7, 7
	v_writelane_b32 v201, s8, 8
	v_writelane_b32 v201, s9, 9
	v_writelane_b32 v201, s10, 10
	v_writelane_b32 v201, s11, 11
	v_writelane_b32 v201, s12, 12
	v_writelane_b32 v201, s13, 13
	v_writelane_b32 v201, s14, 14
	v_writelane_b32 v201, s15, 15
	v_writelane_b32 v201, s16, 16
	v_writelane_b32 v201, s17, 17
	v_writelane_b32 v201, s18, 18
	v_writelane_b32 v201, s19, 19
	v_writelane_b32 v201, s20, 20
	v_writelane_b32 v201, s21, 21
	v_writelane_b32 v201, s22, 22
	v_writelane_b32 v201, s23, 23
	v_writelane_b32 v201, s24, 24
	v_writelane_b32 v201, s25, 25
	v_writelane_b32 v201, s26, 26
	v_writelane_b32 v201, s27, 27
	v_writelane_b32 v201, s28, 28
	v_writelane_b32 v201, s29, 29
	v_writelane_b32 v201, s30, 30
	v_writelane_b32 v201, s31, 31
	v_writelane_b32 v201, s32, 32
	v_writelane_b32 v201, s33, 33
	v_writelane_b32 v201, s34, 34
	v_writelane_b32 v201, s35, 35
	v_writelane_b32 v201, s36, 36
	v_writelane_b32 v201, s37, 37
	v_writelane_b32 v201, s38, 38
	v_writelane_b32 v201, s39, 39
	v_writelane_b32 v201, s40, 40
	v_writelane_b32 v201, s41, 41
	v_writelane_b32 v201, s42, 42
	v_writelane_b32 v201, s43, 43
	v_writelane_b32 v201, s44, 44
	v_writelane_b32 v201, s45, 45
	v_writelane_b32 v201, s46, 46
	v_writelane_b32 v201, s47, 47
	v_writelane_b32 v201, s48, 48
	v_writelane_b32 v201, s49, 49
	v_writelane_b32 v201, s50, 50
	v_writelane_b32 v201, s51, 51
	v_writelane_b32 v201, s52, 52
	v_writelane_b32 v201, s53, 53
	v_writelane_b32 v201, s54, 54
	v_writelane_b32 v201, s55, 55
	v_writelane_b32 v201, s56, 56
	v_writelane_b32 v201, s57, 57
	v_writelane_b32 v201, s58, 58
	v_writelane_b32 v201, s59, 59
	v_writelane_b32 v201, s60, 60
	v_writelane_b32 v201, s61, 61
	v_writelane_b32 v201, s62, 62
	v_writelane_b32 v201, s63, 63
	v_writelane_b32 v202, s64, 0
	v_writelane_b32 v202, s65, 1
	v_writelane_b32 v202, s66, 2
	v_writelane_b32 v202, s67, 3
	v_writelane_b32 v202, s68, 4
	v_writelane_b32 v202, s69, 5
	v_writelane_b32 v202, s70, 6
	v_writelane_b32 v202, s71, 7
	v_writelane_b32 v202, s72, 8
	v_writelane_b32 v202, s73, 9
	v_writelane_b32 v202, s74, 10
	v_writelane_b32 v202, s75, 11
	v_writelane_b32 v202, s76, 12
	v_writelane_b32 v202, s77, 13
	v_writelane_b32 v202, s78, 14
	v_writelane_b32 v202, s79, 15
	v_writelane_b32 v202, s80, 16
	v_writelane_b32 v202, s81, 17
	v_writelane_b32 v202, s82, 18
	v_writelane_b32 v202, s83, 19
	v_writelane_b32 v202, s84, 20
	v_writelane_b32 v202, s85, 21
	v_writelane_b32 v202, s86, 22
	v_writelane_b32 v202, s87, 23
	v_writelane_b32 v202, s88, 24
	v_writelane_b32 v202, s89, 25
	v_writelane_b32 v202, s90, 26
	v_writelane_b32 v202, s91, 27
	v_writelane_b32 v202, s92, 28
	v_writelane_b32 v202, s93, 29
	v_writelane_b32 v202, s94, 30
	v_writelane_b32 v202, s95, 31
	v_writelane_b32 v202, s96, 32
	v_writelane_b32 v202, s97, 33
	v_writelane_b32 v202, s98, 34
	v_writelane_b32 v202, s99, 35
	v_mov_b32_e32 v200, v1
	s_mov_b32 s54, 10608
	s_mov_b32 s52, 12591
	s_cmp_lg_u32 vcc_lo, 0
	s_cbranch_scc0 .Lsj_par4
	s_mov_b32 s54, 3808
	s_mov_b32 s52, 5791

; DEVI const float* IN(int i) { return *(const float* const __attribute__((address_space(4)))*)(kargs() + 8 * i); }
; DEVI void prologue(int wv, LAS unsigned char* lds) {
;     ...
;     for (int it = gw; it < 2 * I_L; it += NGW) {
;         const int l = it / I_L; int r = it % I_L;
;         unsigned char* wl = ws + O_W + (size_t)l * W_LAYER;
;         if (r < I_IN) { const int kb = r / 101, nb = r % 101, n0 = nb * 32;
;             const int d0 = n0 < 384 ? n0 : n0 < 640 ? 512 + (n0 - 384) : n0 < 672 ? 384 + (n0 - 640) : n0 < 1184 ? 768 + (n0 - 672) : n0 < 2208 ? 1280 + (n0 - 1184) : 2304 + (n0 - 2208);
;             tr_item(IN(6) + (size_t)l * 1024 * 3232, 3232, 1024, IN(5) + l * 1024, (bf16_t*)(wl + W_IN), d0, scr, kb * 64, n0, lane); continue; }
;         r -= I_IN;
;         if (r < I_UQ) { const int kb = r / 24, nb = r % 24, n0 = nb * 32, hd = n0 / 96, dim0 = n0 % 96;
;             const int d0 = dim0 < 64 ? 256 * (hd >> 2) + 128 * (dim0 >> 5) + 32 * (hd & 3) : 512 + 128 * (hd >> 2) + 32 * (hd & 3);
;             tr_item(IN(9) + (size_t)l * 384 * 768, 768, 384, IN(7) + l * 384, (bf16_t*)(wl + W_UQ), d0, scr, kb * 64, n0, lane); continue; }
;         r -= I_UQ;
;         if (r < 2 * I_KV) { const int fold = r < I_KV; if (!fold) r -= I_KV;
;             const int kb = r / 32, nb = r % 32, n0 = nb * 32, hd = n0 / 128, dim0 = n0 % 128;
;             const bool isk = dim0 < 64;
;             const int d0 = isk ? 256 * (hd >> 2) + 128 * (dim0 >> 5) + 32 * (hd & 3) : hd * 64 + (dim0 - 64);
;             bf16_t* dst = (bf16_t*)(wl + (fold ? (isk ? W_K : W_V) : (isk ? W_KC : W_VC)));
;             tr_item(IN(10) + (size_t)l * 256 * 1024, 1024, 256, fold ? IN(8) + l * 256 : nullptr, dst, d0, scr, kb * 64, n0, lane); continue; }
;         r -= 2 * I_KV;
;         if (r < I_A) { tr_item(IN(13) + (size_t)l * 512 * 1024, 1024, 512, nullptr, (bf16_t*)(wl + W_A), (r % 32) * 32, scr, (r / 32) * 64, (r % 32) * 32, lane); continue; }
;         r -= I_A;
;         if (r < I_O) { tr_item(IN(17) + (size_t)l * 1024 * 1024, 1024, 1024, nullptr, (bf16_t*)(wl + W_O), (r % 32) * 32, scr, (r / 32) * 64, (r % 32) * 32, lane); continue; }
;         r -= I_O;
;         if (r < I_UP) { tr_item(IN(19) + (size_t)l * 1024 * 4096, 4096, 1024, IN(18) + l * 1024, (bf16_t*)(wl + W_UP), (r % 128) * 32, scr, (r / 128) * 64, (r % 128) * 32, lane); continue; }
;         r -= I_UP;
.LBB0_1559:
	s_waitcnt vmcnt(0) lgkmcnt(0)
	s_load_dword vcc_lo, s[0:1], 0xb8
	v_readlane_b32 vcc_hi, v255, 5
	s_waitcnt lgkmcnt(0)
	s_cmp_lg_u32 vcc_lo, 0x100
	s_cbranch_scc1 .Lsj_skip5
	s_sub_i32 vcc_hi, vcc_hi, 56
	s_and_b32 vcc_hi, vcc_hi, 0xff
	s_cmp_ge_u32 vcc_hi, 248
	s_cbranch_scc1 .Lsj_skip5
	v_readlane_b32 vcc_lo, v255, 0
	v_writelane_b32 v201, s0, 0
	v_writelane_b32 v201, s1, 1
	v_writelane_b32 v201, s2, 2
	v_writelane_b32 v201, s3, 3
	v_writelane_b32 v201, s4, 4
	v_writelane_b32 v201, s5, 5
	v_writelane_b32 v201, s6, 6
	v_writelane_b32 v201, s7, 7
	v_writelane_b32 v201, s8, 8
	v_writelane_b32 v201, s9, 9
	v_writelane_b32 v201, s10, 10
	v_writelane_b32 v201, s11, 11
	v_writelane_b32 v201, s12, 12
	v_writelane_b32 v201, s13, 13
	v_writelane_b32 v201, s14, 14
	v_writelane_b32 v201, s15, 15
	v_writelane_b32 v201, s16, 16
	v_writelane_b32 v201, s17, 17
	v_writelane_b32 v201, s18, 18
	v_writelane_b32 v201, s19, 19
	v_writelane_b32 v201, s20, 20
	v_writelane_b32 v201, s21, 21
	v_writelane_b32 v201, s22, 22
	v_writelane_b32 v201, s23, 23
	v_writelane_b32 v201, s24, 24
	v_writelane_b32 v201, s25, 25
	v_writelane_b32 v201, s26, 26
	v_writelane_b32 v201, s27, 27
	v_writelane_b32 v201, s28, 28
	v_writelane_b32 v201, s29, 29
	v_writelane_b32 v201, s30, 30
	v_writelane_b32 v201, s31, 31
	v_writelane_b32 v201, s32, 32
	v_writelane_b32 v201, s33, 33
	v_writelane_b32 v201, s34, 34
	v_writelane_b32 v201, s35, 35
	v_writelane_b32 v201, s36, 36
	v_writelane_b32 v201, s37, 37
	v_writelane_b32 v201, s38, 38
	v_writelane_b32 v201, s39, 39
	v_writelane_b32 v201, s40, 40
	v_writelane_b32 v201, s41, 41
	v_writelane_b32 v201, s42, 42
	v_writelane_b32 v201, s43, 43
	v_writelane_b32 v201, s44, 44
	v_writelane_b32 v201, s45, 45
	v_writelane_b32 v201, s46, 46
	v_writelane_b32 v201, s47, 47
	v_writelane_b32 v201, s48, 48
	v_writelane_b32 v201, s49, 49
	v_writelane_b32 v201, s50, 50
	v_writelane_b32 v201, s51, 51
	v_writelane_b32 v201, s52, 52
	v_writelane_b32 v201, s53, 53
	v_writelane_b32 v201, s54, 54
	v_writelane_b32 v201, s55, 55
	v_writelane_b32 v201, s56, 56
	v_writelane_b32 v201, s57, 57
	v_writelane_b32 v201, s58, 58
	v_writelane_b32 v201, s59, 59
	v_writelane_b32 v201, s60, 60
	v_writelane_b32 v201, s61, 61
	v_writelane_b32 v201, s62, 62
	v_writelane_b32 v201, s63, 63
	v_writelane_b32 v202, s64, 0
	v_writelane_b32 v202, s65, 1
	v_writelane_b32 v202, s66, 2
	v_writelane_b32 v202, s67, 3
	v_writelane_b32 v202, s68, 4
	v_writelane_b32 v202, s69, 5
	v_writelane_b32 v202, s70, 6
	v_writelane_b32 v202, s71, 7
	v_writelane_b32 v202, s72, 8
	v_writelane_b32 v202, s73, 9
	v_writelane_b32 v202, s74, 10
	v_writelane_b32 v202, s75, 11
	v_writelane_b32 v202, s76, 12
	v_writelane_b32 v202, s77, 13
	v_writelane_b32 v202, s78, 14
	v_writelane_b32 v202, s79, 15
	v_writelane_b32 v202, s80, 16
	v_writelane_b32 v202, s81, 17
	v_writelane_b32 v202, s82, 18
	v_writelane_b32 v202, s83, 19
	v_writelane_b32 v202, s84, 20
	v_writelane_b32 v202, s85, 21
	v_writelane_b32 v202, s86, 22
	v_writelane_b32 v202, s87, 23
	v_writelane_b32 v202, s88, 24
	v_writelane_b32 v202, s89, 25
	v_writelane_b32 v202, s90, 26
	v_writelane_b32 v202, s91, 27
	v_writelane_b32 v202, s92, 28
	v_writelane_b32 v202, s93, 29
	v_writelane_b32 v202, s94, 30
	v_writelane_b32 v202, s95, 31
	v_writelane_b32 v202, s96, 32
	v_writelane_b32 v202, s97, 33
	v_writelane_b32 v202, s98, 34
	v_writelane_b32 v202, s99, 35
	v_mov_b32_e32 v200, v1
	s_mov_b32 s54, 12592
	s_mov_b32 s52, 13759
	s_cmp_lg_u32 vcc_lo, 0
	s_cbranch_scc0 .Lsj_par5
	s_mov_b32 s54, 5792
	s_mov_b32 s52, 9663
